# first barrier uses the XCD barrier instead of cg grid.sync; FFN1 epilogue: both conv-weight staging loads issued before one wait, 256 dead zero-inits before full-mask DPP movs removed
# speedup vs baseline: 1.0292x; 1.0114x over previous
.LBB0_73:
	s_mov_b32 s30, s75
	v_mov_b32_e32 v133, v181
	s_mov_b32 s1, s85
	v_mov_b32_e32 v132, v185
	s_lshl_b32 s0, s30, 8
	s_lshl_b32 s23, s1, 6
	v_lshlrev_b32_e32 v122, 4, v133
	s_add_i32 s0, s0, s23
	v_add3_u32 v134, s0, v132, v122
	v_bfe_i32 v122, v134, 7, 1
	v_and_b32_e32 v122, 0xb00, v122
	s_lshl_b32 s0, s22, 7
	v_add_u32_e32 v122, s0, v122
	s_movk_i32 s22, 0x7f
	v_and_or_b32 v122, v134, s22, v122
	v_ashrrev_i32_e32 v123, 31, v122
	v_lshlrev_b64 v[124:125], 2, v[122:123]
	v_lshl_add_u64 v[122:123], s[12:13], 0, v[124:125]
	v_ashrrev_i32_e32 v135, 8, v134
	v_lshl_add_u64 v[124:125], s[10:11], 0, v[124:125]
	v_cmp_gt_i32_e32 vcc, 3, v135
	v_mov_b64_e32 v[130:131], v[122:123]
	s_and_saveexec_b64 s[22:23], vcc
	v_mul_hi_i32_i24_e32 v131, 0x5800, v135
	v_mul_i32_i24_e32 v130, 0x5800, v135
	v_lshl_add_u64 v[130:131], v[124:125], 0, v[130:131]
	s_or_b64 exec, exec, s[22:23]
	global_load_dword v135, v[130:131], off
	v_add_u32_e32 v131, 0x200, v134
	v_lshl_add_u32 v130, v134, 2, 0
	v_ashrrev_i32_e32 v131, 8, v131
	v_add_u32_e32 v130, 0x22400, v130
	v_cmp_gt_i32_e32 vcc, 3, v131
	s_and_saveexec_b64 s[22:23], vcc
	v_mul_hi_i32_i24_e32 v123, 0x5800, v131
	v_mul_i32_i24_e32 v122, 0x5800, v131
	v_lshl_add_u64 v[122:123], v[124:125], 0, v[122:123]
	s_or_b64 exec, exec, s[22:23]
	global_load_dword v122, v[122:123], off
	v_cmp_lt_i32_e32 vcc, 14, v132
	s_waitcnt vmcnt(0)
	ds_write_b32 v130, v135
	ds_write_b32 v130, v122 offset:2048
	v_lshlrev_b32_e32 v122, 3, v133
	v_lshl_add_u32 v172, s1, 5, v122
	s_and_saveexec_b64 s[22:23], vcc
	s_xor_b64 s[22:23], exec, s[22:23]
	s_cbranch_execz .LBB0_81
	v_cmp_eq_u32_e32 vcc, 15, v132
	s_and_saveexec_b64 s[26:27], vcc
	s_cbranch_execz .LBB0_80
	s_lshl_b32 s1, s30, 11
	s_add_i32 s1, s1, 0
	s_add_i32 s1, s1, 0x20000
	v_lshl_add_u32 v122, v172, 2, s1
	ds_write_b128 v122, v[102:105] offset:1024
	ds_write_b128 v122, v[38:41] offset:1040
	ds_write_b128 v122, v[98:101] offset:1536
	ds_write_b128 v122, v[34:37] offset:1552

.LBB0_105:
	s_lshl_b32 s22, s29, 8
	s_lshl_b32 s23, s30, 6
	v_lshl_add_u32 v130, v172, 2, 0
	s_add_i32 s23, s23, s22
	v_add_u32_e32 v190, 0x22400, v130
	v_cmp_eq_u32_e64 s[42:43], 0, v132
	v_cmp_eq_u32_e64 s[40:41], 15, v132
	v_add_u32_e32 v194, s23, v132
	v_mov_b32_dpp v195, v126 row_ror:1 row_mask:0xf bank_mask:0xf
	v_mov_b32_dpp v196, v127 row_ror:1 row_mask:0xf bank_mask:0xf
	v_mov_b32_dpp v197, v128 row_ror:1 row_mask:0xf bank_mask:0xf
	v_mov_b32_dpp v198, v129 row_ror:1 row_mask:0xf bank_mask:0xf
	v_mov_b32_dpp v130, v126 row_ror:15 row_mask:0xf bank_mask:0xf
	v_mov_b32_dpp v131, v127 row_ror:15 row_mask:0xf bank_mask:0xf
	v_mov_b32_dpp v132, v128 row_ror:15 row_mask:0xf bank_mask:0xf
	v_mov_b32_dpp v133, v129 row_ror:15 row_mask:0xf bank_mask:0xf
	v_mov_b32_dpp v199, v118 row_ror:15 row_mask:0xf bank_mask:0xf
	v_mov_b32_dpp v200, v119 row_ror:15 row_mask:0xf bank_mask:0xf
	v_mov_b32_dpp v201, v120 row_ror:15 row_mask:0xf bank_mask:0xf
	v_mov_b32_dpp v217, v121 row_ror:15 row_mask:0xf bank_mask:0xf
	s_waitcnt lgkmcnt(0)
	v_cndmask_b32_e64 v135, v196, v123, s[42:43]
	v_cndmask_b32_e64 v134, v195, v122, s[42:43]
	v_cndmask_b32_e64 v137, v198, v125, s[42:43]
	v_cndmask_b32_e64 v136, v197, v124, s[42:43]
	v_cndmask_b32_e64 v143, v131, v200, s[40:41]
	v_cndmask_b32_e64 v142, v130, v199, s[40:41]
	v_cndmask_b32_e64 v145, v133, v217, s[40:41]
	v_cndmask_b32_e64 v144, v132, v201, s[40:41]
	ds_read_b128 v[122:125], v190
	ds_read_b128 v[130:133], v190 offset:1024
	s_waitcnt lgkmcnt(0)
	v_pk_mul_f32 v[128:129], v[128:129], v[132:133]
	v_pk_mul_f32 v[126:127], v[126:127], v[130:131]
	v_pk_fma_f32 v[136:137], v[136:137], v[124:125], v[128:129]
	v_pk_fma_f32 v[134:135], v[134:135], v[122:123], v[126:127]
	ds_read_b128 v[126:129], v190 offset:2048
	s_waitcnt lgkmcnt(0)
	v_pk_fma_f32 v[144:145], v[128:129], v[144:145], v[136:137]
	v_pk_fma_f32 v[142:143], v[126:127], v[142:143], v[134:135]
	ds_read_b128 v[134:137], v190 offset:3072
	v_mov_b32_dpp v218, v146 row_ror:1 row_mask:0xf bank_mask:0xf
	v_mov_b32_dpp v219, v147 row_ror:1 row_mask:0xf bank_mask:0xf
	v_mov_b32_dpp v220, v148 row_ror:1 row_mask:0xf bank_mask:0xf
	v_mov_b32_dpp v221, v149 row_ror:1 row_mask:0xf bank_mask:0xf
	s_waitcnt lgkmcnt(0)
	v_pk_add_f32 v[174:175], v[136:137], v[144:145]
	v_pk_add_f32 v[176:177], v[134:135], v[142:143]
	v_mov_b32_dpp v142, v146 row_ror:15 row_mask:0xf bank_mask:0xf
	v_mov_b32_dpp v143, v147 row_ror:15 row_mask:0xf bank_mask:0xf
	v_mov_b32_dpp v144, v148 row_ror:15 row_mask:0xf bank_mask:0xf
	v_mov_b32_dpp v145, v149 row_ror:15 row_mask:0xf bank_mask:0xf
	v_mov_b32_dpp v222, v114 row_ror:15 row_mask:0xf bank_mask:0xf
	v_mov_b32_dpp v223, v115 row_ror:15 row_mask:0xf bank_mask:0xf
	v_mov_b32_dpp v224, v116 row_ror:15 row_mask:0xf bank_mask:0xf
	v_mov_b32_dpp v225, v117 row_ror:15 row_mask:0xf bank_mask:0xf
	v_cndmask_b32_e64 v151, v219, v139, s[42:43]
	v_cndmask_b32_e64 v150, v218, v138, s[42:43]
	v_cndmask_b32_e64 v153, v221, v141, s[42:43]
	v_cndmask_b32_e64 v152, v220, v140, s[42:43]
	v_cndmask_b32_e64 v209, v143, v223, s[40:41]
	v_cndmask_b32_e64 v208, v142, v222, s[40:41]
	v_cndmask_b32_e64 v213, v145, v225, s[40:41]
	v_cndmask_b32_e64 v212, v144, v224, s[40:41]
	ds_read_b128 v[138:141], v190 offset:512
	ds_read_b128 v[142:145], v190 offset:1536
	v_mul_f32_e32 v214, 0xbfb8aa3b, v176
	v_mul_f32_e32 v215, 0xbfb8aa3b, v177
	v_exp_f32_e32 v214, v214
	v_exp_f32_e32 v215, v215
	s_waitcnt lgkmcnt(0)
	v_pk_mul_f32 v[148:149], v[148:149], v[144:145]
	v_pk_mul_f32 v[146:147], v[146:147], v[142:143]
	v_pk_fma_f32 v[152:153], v[152:153], v[140:141], v[148:149]
	v_pk_fma_f32 v[150:151], v[150:151], v[138:139], v[146:147]
	ds_read_b128 v[146:149], v190 offset:2560
	v_add_f32_e32 v214, 1.0, v214
	v_add_f32_e32 v215, 1.0, v215
	v_rcp_f32_e32 v214, v214
	v_rcp_f32_e32 v215, v215
	s_waitcnt lgkmcnt(0)
	v_pk_fma_f32 v[212:213], v[148:149], v[212:213], v[152:153]
	v_pk_fma_f32 v[208:209], v[146:147], v[208:209], v[150:151]
	ds_read_b128 v[150:153], v190 offset:3584
	v_pk_mul_f32 v[176:177], v[176:177], v[214:215]
	s_lshl_b64 s[0:1], s[0:1], 1
	s_waitcnt lgkmcnt(0)
	v_pk_add_f32 v[208:209], v[150:151], v[208:209]
	v_pk_add_f32 v[212:213], v[152:153], v[212:213]
	v_pk_mul_f32 v[176:177], v[176:177], v[208:209]
	v_mov_b32_dpp v216, v120 row_ror:1 row_mask:0xf bank_mask:0xf
	v_cvt_pk_bf16_f32 v208, v176, v177
	v_mul_f32_e32 v176, 0xbfb8aa3b, v174
	v_mul_f32_e32 v177, 0xbfb8aa3b, v175
	v_exp_f32_e32 v176, v176
	v_exp_f32_e32 v177, v177
	v_mov_b32_dpp v226, v121 row_ror:1 row_mask:0xf bank_mask:0xf
	v_add_f32_e32 v176, 1.0, v176
	v_add_f32_e32 v177, 1.0, v177
	v_rcp_f32_e32 v176, v176
	v_rcp_f32_e32 v177, v177
	s_nop 0
	v_pk_mul_f32 v[174:175], v[174:175], v[176:177]
	v_mov_b64_e32 v[176:177], s[16:17]
	v_pk_mul_f32 v[174:175], v[174:175], v[212:213]
	v_cvt_pk_bf16_f32 v209, v174, v175
	v_mad_i64_i32 v[174:175], s[22:23], v194, s15, v[176:177]
	v_lshl_add_u64 v[212:213], v[174:175], 0, s[0:1]
	v_lshlrev_b64 v[174:175], 1, v[172:173]
	v_lshl_add_u64 v[172:173], v[212:213], 0, v[174:175]
	global_store_dwordx2 v[172:173], v[208:209], off
	v_mov_b32_dpp v227, v110 row_ror:15 row_mask:0xf bank_mask:0xf
	v_mov_b32_dpp v228, v111 row_ror:15 row_mask:0xf bank_mask:0xf
	v_mov_b32_dpp v229, v112 row_ror:15 row_mask:0xf bank_mask:0xf
	v_cndmask_b32_e64 v209, v226, v198, s[42:43]
	v_cndmask_b32_e64 v208, v216, v197, s[42:43]
	v_mov_b32_dpp v214, v118 row_ror:1 row_mask:0xf bank_mask:0xf
	v_mov_b32_dpp v215, v119 row_ror:1 row_mask:0xf bank_mask:0xf
	v_mov_b32_dpp v230, v113 row_ror:15 row_mask:0xf bank_mask:0xf
	v_cndmask_b32_e64 v212, v201, v229, s[40:41]
	v_cndmask_b32_e64 v201, v200, v228, s[40:41]
	v_cndmask_b32_e64 v200, v199, v227, s[40:41]
	v_pk_mul_f32 v[198:199], v[124:125], v[208:209]
	v_cndmask_b32_e64 v197, v215, v196, s[42:43]
	v_cndmask_b32_e64 v196, v214, v195, s[42:43]
	v_cndmask_b32_e64 v213, v217, v230, s[40:41]
	v_pk_fma_f32 v[120:121], v[120:121], v[132:133], v[198:199]
	v_pk_mul_f32 v[196:197], v[122:123], v[196:197]
	v_pk_fma_f32 v[120:121], v[128:129], v[212:213], v[120:121]
	v_pk_fma_f32 v[118:119], v[118:119], v[130:131], v[196:197]
	v_mov_b32_dpp v213, v116 row_ror:1 row_mask:0xf bank_mask:0xf
	v_mov_b32_dpp v217, v117 row_ror:1 row_mask:0xf bank_mask:0xf
	v_pk_fma_f32 v[118:119], v[126:127], v[200:201], v[118:119]
	v_cndmask_b32_e64 v197, v217, v221, s[42:43]
	v_cndmask_b32_e64 v196, v213, v220, s[42:43]
	v_pk_add_f32 v[118:119], v[134:135], v[118:119]
	v_pk_mul_f32 v[196:197], v[140:141], v[196:197]
	v_pk_fma_f32 v[116:117], v[116:117], v[144:145], v[196:197]
	v_mul_f32_e32 v196, 0xbfb8aa3b, v118
	v_mul_f32_e32 v197, 0xbfb8aa3b, v119
	v_exp_f32_e32 v196, v196
	v_exp_f32_e32 v197, v197
	v_mov_b32_dpp v195, v114 row_ror:1 row_mask:0xf bank_mask:0xf
	v_add_f32_e32 v196, 1.0, v196
	v_mov_b32_dpp v212, v115 row_ror:1 row_mask:0xf bank_mask:0xf
	v_add_f32_e32 v197, 1.0, v197
	v_cndmask_b32_e64 v199, v212, v219, s[42:43]
	v_cndmask_b32_e64 v198, v195, v218, s[42:43]
	v_rcp_f32_e32 v196, v196
	v_rcp_f32_e32 v197, v197
	v_mov_b32_dpp v231, v106 row_ror:15 row_mask:0xf bank_mask:0xf
	v_mov_b32_dpp v232, v107 row_ror:15 row_mask:0xf bank_mask:0xf
	v_pk_mul_f32 v[198:199], v[138:139], v[198:199]
	v_cndmask_b32_e64 v209, v223, v232, s[40:41]
	v_cndmask_b32_e64 v208, v222, v231, s[40:41]
	v_pk_fma_f32 v[114:115], v[114:115], v[142:143], v[198:199]
	v_pk_mul_f32 v[118:119], v[118:119], v[196:197]
	v_pk_fma_f32 v[114:115], v[146:147], v[208:209], v[114:115]
	v_pk_add_f32 v[120:121], v[136:137], v[120:121]
	v_pk_add_f32 v[114:115], v[150:151], v[114:115]
	v_pk_mul_f32 v[114:115], v[118:119], v[114:115]
	v_cvt_pk_bf16_f32 v118, v114, v115
	v_mul_f32_e32 v114, 0xbfb8aa3b, v120
	v_mul_f32_e32 v115, 0xbfb8aa3b, v121
	v_exp_f32_e32 v114, v114
	v_exp_f32_e32 v115, v115
	v_mov_b32_dpp v233, v108 row_ror:15 row_mask:0xf bank_mask:0xf
	v_mov_b32_dpp v234, v109 row_ror:15 row_mask:0xf bank_mask:0xf
	v_add_f32_e32 v114, 1.0, v114
	v_add_f32_e32 v115, 1.0, v115
	v_rcp_f32_e32 v114, v114
	v_rcp_f32_e32 v115, v115
	v_cndmask_b32_e64 v201, v225, v234, s[40:41]
	v_cndmask_b32_e64 v200, v224, v233, s[40:41]
	v_pk_fma_f32 v[116:117], v[148:149], v[200:201], v[116:117]
	v_pk_mul_f32 v[114:115], v[120:121], v[114:115]
	v_pk_add_f32 v[116:117], v[152:153], v[116:117]
	v_pk_mul_f32 v[114:115], v[114:115], v[116:117]
	v_cvt_pk_bf16_f32 v119, v114, v115
	v_add_u32_e32 v114, 16, v194
	v_mad_i64_i32 v[114:115], s[22:23], v114, s15, v[176:177]
	v_lshl_add_u64 v[114:115], v[114:115], 0, s[0:1]
	v_lshl_add_u64 v[114:115], v[114:115], 0, v[174:175]
	v_mov_b32_dpp v198, v110 row_ror:1 row_mask:0xf bank_mask:0xf
	v_mov_b32_dpp v199, v111 row_ror:1 row_mask:0xf bank_mask:0xf
	global_store_dwordx2 v[114:115], v[118:119], off
	v_mov_b32_dpp v200, v112 row_ror:1 row_mask:0xf bank_mask:0xf
	v_mov_b32_dpp v201, v113 row_ror:1 row_mask:0xf bank_mask:0xf
	v_cndmask_b32_e64 v119, v199, v215, s[42:43]
	v_cndmask_b32_e64 v118, v198, v214, s[42:43]
	v_mov_b32_dpp v208, v102 row_ror:15 row_mask:0xf bank_mask:0xf
	v_mov_b32_dpp v209, v103 row_ror:15 row_mask:0xf bank_mask:0xf
	v_cndmask_b32_e64 v117, v201, v226, s[42:43]
	v_cndmask_b32_e64 v116, v200, v216, s[42:43]
	v_pk_mul_f32 v[118:119], v[122:123], v[118:119]
	v_cndmask_b32_e64 v197, v228, v209, s[40:41]
	v_cndmask_b32_e64 v196, v227, v208, s[40:41]
	v_pk_mul_f32 v[116:117], v[124:125], v[116:117]
	v_pk_fma_f32 v[110:111], v[110:111], v[130:131], v[118:119]
	v_mov_b32_dpp v216, v108 row_ror:1 row_mask:0xf bank_mask:0xf
	v_mov_b32_dpp v220, v109 row_ror:1 row_mask:0xf bank_mask:0xf
	v_pk_fma_f32 v[112:113], v[112:113], v[132:133], v[116:117]
	v_pk_fma_f32 v[110:111], v[126:127], v[196:197], v[110:111]
	v_cndmask_b32_e64 v117, v220, v217, s[42:43]
	v_cndmask_b32_e64 v116, v216, v213, s[42:43]
	v_pk_add_f32 v[110:111], v[134:135], v[110:111]
	v_pk_mul_f32 v[116:117], v[140:141], v[116:117]
	v_pk_fma_f32 v[108:109], v[108:109], v[144:145], v[116:117]
	v_mul_f32_e32 v116, 0xbfb8aa3b, v110
	v_mul_f32_e32 v117, 0xbfb8aa3b, v111
	v_exp_f32_e32 v116, v116
	v_exp_f32_e32 v117, v117
	v_mov_b32_dpp v214, v106 row_ror:1 row_mask:0xf bank_mask:0xf
	v_add_f32_e32 v116, 1.0, v116
	v_mov_b32_dpp v215, v107 row_ror:1 row_mask:0xf bank_mask:0xf
	v_add_f32_e32 v117, 1.0, v117
	v_cndmask_b32_e64 v119, v215, v212, s[42:43]
	v_cndmask_b32_e64 v118, v214, v195, s[42:43]
	v_rcp_f32_e32 v116, v116
	v_rcp_f32_e32 v117, v117
	v_mov_b32_dpp v221, v98 row_ror:15 row_mask:0xf bank_mask:0xf
	v_mov_b32_dpp v222, v99 row_ror:15 row_mask:0xf bank_mask:0xf
	v_pk_mul_f32 v[118:119], v[138:139], v[118:119]
	v_mov_b32_dpp v218, v104 row_ror:15 row_mask:0xf bank_mask:0xf
	v_mov_b32_dpp v219, v105 row_ror:15 row_mask:0xf bank_mask:0xf
	v_cndmask_b32_e64 v197, v232, v222, s[40:41]
	v_cndmask_b32_e64 v196, v231, v221, s[40:41]
	v_pk_fma_f32 v[106:107], v[106:107], v[142:143], v[118:119]
	v_cndmask_b32_e64 v121, v230, v219, s[40:41]
	v_cndmask_b32_e64 v120, v229, v218, s[40:41]
	v_pk_fma_f32 v[106:107], v[146:147], v[196:197], v[106:107]
	v_pk_fma_f32 v[112:113], v[128:129], v[120:121], v[112:113]
	v_pk_add_f32 v[106:107], v[150:151], v[106:107]
	v_pk_mul_f32 v[110:111], v[110:111], v[116:117]
	v_pk_add_f32 v[112:113], v[136:137], v[112:113]
	v_pk_mul_f32 v[106:107], v[110:111], v[106:107]
	v_cvt_pk_bf16_f32 v106, v106, v107
	v_mul_f32_e32 v107, 0xbfb8aa3b, v112
	v_exp_f32_e32 v107, v107
	v_mov_b32_dpp v223, v100 row_ror:15 row_mask:0xf bank_mask:0xf
	v_cndmask_b32_e64 v120, v233, v223, s[40:41]
	v_add_f32_e32 v107, 1.0, v107
	v_rcp_f32_e32 v110, v107
	v_mul_f32_e32 v107, 0xbfb8aa3b, v113
	v_exp_f32_e32 v107, v107
	v_mov_b32_dpp v224, v101 row_ror:15 row_mask:0xf bank_mask:0xf
	v_cndmask_b32_e64 v121, v234, v224, s[40:41]
	v_pk_fma_f32 v[108:109], v[148:149], v[120:121], v[108:109]
	v_add_f32_e32 v107, 1.0, v107
	v_rcp_f32_e32 v111, v107
	v_pk_add_f32 v[108:109], v[152:153], v[108:109]
	s_cmp_gt_i32 s30, -2
	v_pk_mul_f32 v[110:111], v[112:113], v[110:111]
	s_nop 0
	v_pk_mul_f32 v[108:109], v[110:111], v[108:109]
	v_cndmask_b32_e64 v113, v209, v155, s[40:41]
	v_cvt_pk_bf16_f32 v107, v108, v109
	v_add_u32_e32 v108, 32, v194
	v_mad_i64_i32 v[108:109], s[22:23], v108, s15, v[176:177]
	v_lshl_add_u64 v[108:109], v[108:109], 0, s[0:1]
	v_lshl_add_u64 v[116:117], v[108:109], 0, v[174:175]
	global_store_dwordx2 v[116:117], v[106:107], off
	v_mov_b32_dpp v106, v104 row_ror:1 row_mask:0xf bank_mask:0xf
	v_mov_b32_dpp v107, v105 row_ror:1 row_mask:0xf bank_mask:0xf
	v_mov_b32_dpp v108, v102 row_ror:1 row_mask:0xf bank_mask:0xf
	v_mov_b32_dpp v109, v103 row_ror:1 row_mask:0xf bank_mask:0xf
	v_cndmask_b32_e64 v107, v107, v201, s[42:43]
	v_cndmask_b32_e64 v106, v106, v200, s[42:43]
	v_cndmask_b32_e64 v109, v109, v199, s[42:43]
	v_cndmask_b32_e64 v108, v108, v198, s[42:43]
	v_pk_mul_f32 v[106:107], v[124:125], v[106:107]
	v_pk_mul_f32 v[108:109], v[122:123], v[108:109]
	v_pk_fma_f32 v[104:105], v[104:105], v[132:133], v[106:107]
	v_cndmask_b32_e64 v112, v208, v154, s[40:41]
	v_pk_fma_f32 v[102:103], v[102:103], v[130:131], v[108:109]
	v_mov_b32_dpp v106, v100 row_ror:1 row_mask:0xf bank_mask:0xf
	v_mov_b32_dpp v107, v101 row_ror:1 row_mask:0xf bank_mask:0xf
	v_pk_fma_f32 v[102:103], v[126:127], v[112:113], v[102:103]
	v_cndmask_b32_e64 v107, v107, v220, s[42:43]
	v_cndmask_b32_e64 v106, v106, v216, s[42:43]
	v_pk_add_f32 v[102:103], v[134:135], v[102:103]
	v_pk_mul_f32 v[106:107], v[140:141], v[106:107]
	v_pk_fma_f32 v[100:101], v[100:101], v[144:145], v[106:107]
	v_mul_f32_e32 v106, 0xbfb8aa3b, v102
	v_mul_f32_e32 v107, 0xbfb8aa3b, v103
	v_exp_f32_e32 v106, v106
	v_exp_f32_e32 v107, v107
	v_mov_b32_dpp v108, v98 row_ror:1 row_mask:0xf bank_mask:0xf
	v_add_f32_e32 v106, 1.0, v106
	v_mov_b32_dpp v109, v99 row_ror:1 row_mask:0xf bank_mask:0xf
	v_add_f32_e32 v107, 1.0, v107
	v_cndmask_b32_e64 v109, v109, v215, s[42:43]
	v_cndmask_b32_e64 v108, v108, v214, s[42:43]
	v_rcp_f32_e32 v106, v106
	v_rcp_f32_e32 v107, v107
	v_pk_mul_f32 v[108:109], v[138:139], v[108:109]
	v_cndmask_b32_e64 v113, v222, v159, s[40:41]
	v_cndmask_b32_e64 v112, v221, v158, s[40:41]
	v_pk_fma_f32 v[98:99], v[98:99], v[142:143], v[108:109]
	v_cndmask_b32_e64 v111, v219, v157, s[40:41]
	v_cndmask_b32_e64 v110, v218, v156, s[40:41]
	v_pk_fma_f32 v[98:99], v[146:147], v[112:113], v[98:99]
	v_pk_fma_f32 v[104:105], v[128:129], v[110:111], v[104:105]
	v_pk_add_f32 v[98:99], v[150:151], v[98:99]
	v_pk_mul_f32 v[102:103], v[102:103], v[106:107]
	v_pk_add_f32 v[104:105], v[136:137], v[104:105]
	v_pk_mul_f32 v[98:99], v[98:99], v[102:103]
	v_cndmask_b32_e64 v111, v224, v161, s[40:41]
	v_cvt_pk_bf16_f32 v98, v98, v99
	v_mul_f32_e32 v99, 0xbfb8aa3b, v104
	v_exp_f32_e32 v99, v99
	v_cndmask_b32_e64 v110, v223, v160, s[40:41]
	v_pk_fma_f32 v[100:101], v[148:149], v[110:111], v[100:101]
	v_mov_b32_e32 v110, 0
	v_add_f32_e32 v99, 1.0, v99
	v_rcp_f32_e32 v102, v99
	v_mul_f32_e32 v99, 0xbfb8aa3b, v105
	v_exp_f32_e32 v99, v99
	v_pk_add_f32 v[100:101], v[152:153], v[100:101]
	v_mov_b32_e32 v111, 0
	v_mov_b32_e32 v112, 0
	v_add_f32_e32 v99, 1.0, v99
	v_rcp_f32_e32 v103, v99
	v_mov_b32_e32 v113, 0
	v_pk_mul_f32 v[102:103], v[104:105], v[102:103]
	s_nop 0
	v_pk_mul_f32 v[100:101], v[100:101], v[102:103]
	s_nop 0
	v_cvt_pk_bf16_f32 v99, v100, v101
	v_add_u32_e32 v100, 48, v194
	v_mad_i64_i32 v[100:101], s[22:23], v100, s15, v[176:177]
	v_lshl_add_u64 v[100:101], v[100:101], 0, s[0:1]
	s_cselect_b64 s[22:23], -1, 0
	s_lshl_b32 s29, s28, 2
	v_lshl_add_u64 v[118:119], v[100:101], 0, v[174:175]
	s_add_i32 s26, s29, -2
	global_store_dwordx2 v[118:119], v[98:99], off
	s_cmp_lt_i32 s30, -1
	v_mov_b32_e32 v98, 0
	v_lshl_add_u32 v120, s26, 9, v189
	s_cbranch_scc1 .LBB0_107
	ds_read_b128 v[110:113], v120

.LBB0_113:
	v_mov_b32_dpp v160, v96 row_ror:1 row_mask:0xf bank_mask:0xf
	v_mov_b32_dpp v161, v97 row_ror:1 row_mask:0xf bank_mask:0xf
	s_waitcnt lgkmcnt(0)
	v_cndmask_b32_e64 v113, v161, v113, s[42:43]
	v_cndmask_b32_e64 v112, v160, v112, s[42:43]
	v_mov_b32_dpp v158, v94 row_ror:1 row_mask:0xf bank_mask:0xf
	v_mov_b32_dpp v159, v95 row_ror:1 row_mask:0xf bank_mask:0xf
	v_mov_b32_dpp v154, v96 row_ror:15 row_mask:0xf bank_mask:0xf
	v_mov_b32_dpp v155, v97 row_ror:15 row_mask:0xf bank_mask:0xf
	v_mov_b32_dpp v195, v88 row_ror:15 row_mask:0xf bank_mask:0xf
	v_mov_b32_dpp v196, v89 row_ror:15 row_mask:0xf bank_mask:0xf
	v_pk_mul_f32 v[112:113], v[124:125], v[112:113]
	v_cndmask_b32_e64 v111, v159, v111, s[42:43]
	v_cndmask_b32_e64 v110, v158, v110, s[42:43]
	v_cndmask_b32_e64 v155, v155, v196, s[40:41]
	v_cndmask_b32_e64 v154, v154, v195, s[40:41]
	v_pk_fma_f32 v[96:97], v[96:97], v[132:133], v[112:113]
	v_mov_b32_dpp v156, v94 row_ror:15 row_mask:0xf bank_mask:0xf
	v_mov_b32_dpp v157, v95 row_ror:15 row_mask:0xf bank_mask:0xf
	v_mov_b32_dpp v176, v86 row_ror:15 row_mask:0xf bank_mask:0xf
	v_mov_b32_dpp v177, v87 row_ror:15 row_mask:0xf bank_mask:0xf
	v_pk_mul_f32 v[110:111], v[122:123], v[110:111]
	v_pk_fma_f32 v[96:97], v[128:129], v[154:155], v[96:97]
	v_cndmask_b32_e64 v157, v157, v177, s[40:41]
	v_cndmask_b32_e64 v156, v156, v176, s[40:41]
	v_pk_fma_f32 v[94:95], v[94:95], v[130:131], v[110:111]
	v_mov_b32_dpp v154, v90 row_ror:1 row_mask:0xf bank_mask:0xf
	v_mov_b32_dpp v155, v91 row_ror:1 row_mask:0xf bank_mask:0xf
	v_pk_fma_f32 v[94:95], v[126:127], v[156:157], v[94:95]
	v_cndmask_b32_e64 v107, v155, v107, s[42:43]
	v_cndmask_b32_e64 v106, v154, v106, s[42:43]
	v_pk_add_f32 v[94:95], v[134:135], v[94:95]
	v_mov_b32_dpp v156, v92 row_ror:1 row_mask:0xf bank_mask:0xf
	v_mov_b32_dpp v157, v93 row_ror:1 row_mask:0xf bank_mask:0xf
	v_pk_mul_f32 v[106:107], v[138:139], v[106:107]
	v_mov_b32_dpp v112, v90 row_ror:15 row_mask:0xf bank_mask:0xf
	v_mov_b32_dpp v113, v91 row_ror:15 row_mask:0xf bank_mask:0xf
	v_cndmask_b32_e64 v109, v157, v109, s[42:43]
	v_cndmask_b32_e64 v108, v156, v108, s[42:43]
	v_pk_fma_f32 v[90:91], v[90:91], v[142:143], v[106:107]
	v_mul_f32_e32 v106, 0xbfb8aa3b, v94
	v_mul_f32_e32 v107, 0xbfb8aa3b, v95
	v_pk_add_f32 v[96:97], v[136:137], v[96:97]
	v_pk_mul_f32 v[108:109], v[140:141], v[108:109]
	v_exp_f32_e32 v106, v106
	v_exp_f32_e32 v107, v107
	v_mov_b32_dpp v110, v92 row_ror:15 row_mask:0xf bank_mask:0xf
	v_mov_b32_dpp v111, v93 row_ror:15 row_mask:0xf bank_mask:0xf
	v_pk_fma_f32 v[92:93], v[92:93], v[144:145], v[108:109]
	v_mul_f32_e32 v108, 0xbfb8aa3b, v96
	v_mul_f32_e32 v109, 0xbfb8aa3b, v97
	v_exp_f32_e32 v108, v108
	v_exp_f32_e32 v109, v109
	v_add_f32_e32 v106, 1.0, v106
	v_add_f32_e32 v107, 1.0, v107
	v_rcp_f32_e32 v106, v106
	v_rcp_f32_e32 v107, v107
	v_mov_b32_dpp v197, v82 row_ror:15 row_mask:0xf bank_mask:0xf
	v_mov_b32_dpp v198, v83 row_ror:15 row_mask:0xf bank_mask:0xf
	v_add_f32_e32 v108, 1.0, v108
	v_add_f32_e32 v109, 1.0, v109
	v_cndmask_b32_e64 v113, v113, v198, s[40:41]
	v_cndmask_b32_e64 v112, v112, v197, s[40:41]
	v_rcp_f32_e32 v108, v108
	v_rcp_f32_e32 v109, v109
	v_mov_b32_dpp v199, v84 row_ror:15 row_mask:0xf bank_mask:0xf
	v_mov_b32_dpp v200, v85 row_ror:15 row_mask:0xf bank_mask:0xf
	v_pk_fma_f32 v[90:91], v[146:147], v[112:113], v[90:91]
	v_cndmask_b32_e64 v111, v111, v200, s[40:41]
	v_cndmask_b32_e64 v110, v110, v199, s[40:41]
	v_pk_add_f32 v[90:91], v[150:151], v[90:91]
	v_pk_mul_f32 v[94:95], v[94:95], v[106:107]
	v_pk_fma_f32 v[92:93], v[148:149], v[110:111], v[92:93]
	v_pk_mul_f32 v[90:91], v[94:95], v[90:91]
	v_pk_add_f32 v[92:93], v[152:153], v[92:93]
	v_cvt_pk_bf16_f32 v94, v90, v91
	v_pk_mul_f32 v[90:91], v[96:97], v[108:109]
	v_add_u32_e32 v121, 0x80, v194
	v_pk_mul_f32 v[90:91], v[90:91], v[92:93]
	v_cvt_pk_bf16_f32 v95, v90, v91
	v_mov_b64_e32 v[90:91], s[16:17]
	v_mad_i64_i32 v[92:93], s[22:23], v121, s15, v[90:91]
	v_lshl_add_u64 v[92:93], v[92:93], 0, s[0:1]
	v_lshl_add_u64 v[106:107], v[92:93], 0, v[174:175]
	v_mov_b32_dpp v110, v86 row_ror:1 row_mask:0xf bank_mask:0xf
	v_mov_b32_dpp v111, v87 row_ror:1 row_mask:0xf bank_mask:0xf
	global_store_dwordx2 v[106:107], v[94:95], off
	v_mov_b32_dpp v112, v88 row_ror:1 row_mask:0xf bank_mask:0xf
	v_mov_b32_dpp v113, v89 row_ror:1 row_mask:0xf bank_mask:0xf
	v_cndmask_b32_e64 v95, v111, v159, s[42:43]
	v_cndmask_b32_e64 v94, v110, v158, s[42:43]
	v_mov_b32_dpp v121, v78 row_ror:15 row_mask:0xf bank_mask:0xf
	v_mov_b32_dpp v201, v79 row_ror:15 row_mask:0xf bank_mask:0xf
	v_cndmask_b32_e64 v93, v113, v161, s[42:43]
	v_cndmask_b32_e64 v92, v112, v160, s[42:43]
	v_pk_mul_f32 v[94:95], v[122:123], v[94:95]
	v_mov_b32_dpp v208, v80 row_ror:15 row_mask:0xf bank_mask:0xf
	v_mov_b32_dpp v209, v81 row_ror:15 row_mask:0xf bank_mask:0xf
	v_cndmask_b32_e64 v109, v177, v201, s[40:41]
	v_cndmask_b32_e64 v108, v176, v121, s[40:41]
	v_pk_mul_f32 v[92:93], v[124:125], v[92:93]
	v_pk_fma_f32 v[86:87], v[86:87], v[130:131], v[94:95]
	v_mov_b32_dpp v160, v84 row_ror:1 row_mask:0xf bank_mask:0xf
	v_mov_b32_dpp v161, v85 row_ror:1 row_mask:0xf bank_mask:0xf
	v_cndmask_b32_e64 v97, v196, v209, s[40:41]
	v_cndmask_b32_e64 v96, v195, v208, s[40:41]
	v_pk_fma_f32 v[88:89], v[88:89], v[132:133], v[92:93]
	v_pk_fma_f32 v[86:87], v[126:127], v[108:109], v[86:87]
	v_mov_b32_dpp v158, v82 row_ror:1 row_mask:0xf bank_mask:0xf
	v_mov_b32_dpp v159, v83 row_ror:1 row_mask:0xf bank_mask:0xf
	v_cndmask_b32_e64 v93, v161, v157, s[42:43]
	v_cndmask_b32_e64 v92, v160, v156, s[42:43]
	v_pk_fma_f32 v[88:89], v[128:129], v[96:97], v[88:89]
	v_pk_add_f32 v[86:87], v[134:135], v[86:87]
	v_cndmask_b32_e64 v95, v159, v155, s[42:43]
	v_cndmask_b32_e64 v94, v158, v154, s[42:43]
	v_pk_mul_f32 v[92:93], v[140:141], v[92:93]
	v_pk_add_f32 v[88:89], v[136:137], v[88:89]
	v_pk_mul_f32 v[94:95], v[138:139], v[94:95]
	v_pk_fma_f32 v[84:85], v[84:85], v[144:145], v[92:93]
	v_mul_f32_e32 v92, 0xbfb8aa3b, v86
	v_mul_f32_e32 v93, 0xbfb8aa3b, v87
	v_pk_fma_f32 v[82:83], v[82:83], v[142:143], v[94:95]
	v_exp_f32_e32 v92, v92
	v_exp_f32_e32 v93, v93
	v_mul_f32_e32 v94, 0xbfb8aa3b, v88
	v_mul_f32_e32 v95, 0xbfb8aa3b, v89
	v_exp_f32_e32 v94, v94
	v_exp_f32_e32 v95, v95
	v_add_f32_e32 v92, 1.0, v92
	v_add_f32_e32 v93, 1.0, v93
	v_rcp_f32_e32 v92, v92
	v_rcp_f32_e32 v93, v93
	v_add_f32_e32 v94, 1.0, v94
	v_add_f32_e32 v95, 1.0, v95
	v_mov_b32_dpp v176, v74 row_ror:15 row_mask:0xf bank_mask:0xf
	v_mov_b32_dpp v177, v75 row_ror:15 row_mask:0xf bank_mask:0xf
	v_rcp_f32_e32 v94, v94
	v_rcp_f32_e32 v95, v95
	v_mov_b32_dpp v195, v76 row_ror:15 row_mask:0xf bank_mask:0xf
	v_mov_b32_dpp v196, v77 row_ror:15 row_mask:0xf bank_mask:0xf
	v_cndmask_b32_e64 v109, v198, v177, s[40:41]
	v_cndmask_b32_e64 v108, v197, v176, s[40:41]
	v_cndmask_b32_e64 v97, v200, v196, s[40:41]
	v_cndmask_b32_e64 v96, v199, v195, s[40:41]
	v_pk_fma_f32 v[82:83], v[146:147], v[108:109], v[82:83]
	v_pk_fma_f32 v[84:85], v[148:149], v[96:97], v[84:85]
	v_pk_add_f32 v[82:83], v[150:151], v[82:83]
	v_pk_mul_f32 v[86:87], v[86:87], v[92:93]
	v_pk_add_f32 v[84:85], v[152:153], v[84:85]
	v_pk_mul_f32 v[82:83], v[86:87], v[82:83]
	v_pk_mul_f32 v[86:87], v[88:89], v[94:95]
	v_cvt_pk_bf16_f32 v82, v82, v83
	v_pk_mul_f32 v[84:85], v[86:87], v[84:85]
	v_cvt_pk_bf16_f32 v83, v84, v85
	v_add_u32_e32 v84, 0x90, v194
	v_mad_i64_i32 v[84:85], s[22:23], v84, s15, v[90:91]
	v_lshl_add_u64 v[84:85], v[84:85], 0, s[0:1]
	v_mov_b32_dpp v92, v78 row_ror:1 row_mask:0xf bank_mask:0xf
	v_mov_b32_dpp v93, v79 row_ror:1 row_mask:0xf bank_mask:0xf
	v_lshl_add_u64 v[108:109], v[84:85], 0, v[174:175]
	v_mov_b32_dpp v94, v80 row_ror:1 row_mask:0xf bank_mask:0xf
	v_mov_b32_dpp v95, v81 row_ror:1 row_mask:0xf bank_mask:0xf
	v_mov_b32_dpp v96, v70 row_ror:15 row_mask:0xf bank_mask:0xf
	v_cndmask_b32_e64 v85, v93, v111, s[42:43]
	v_cndmask_b32_e64 v84, v92, v110, s[42:43]
	global_store_dwordx2 v[108:109], v[82:83], off
	v_mov_b32_dpp v97, v71 row_ror:15 row_mask:0xf bank_mask:0xf
	v_cndmask_b32_e64 v83, v95, v113, s[42:43]
	v_cndmask_b32_e64 v82, v94, v112, s[42:43]
	v_cndmask_b32_e64 v88, v121, v96, s[40:41]
	v_pk_mul_f32 v[84:85], v[122:123], v[84:85]
	v_mov_b32_dpp v154, v72 row_ror:15 row_mask:0xf bank_mask:0xf
	v_mov_b32_dpp v155, v73 row_ror:15 row_mask:0xf bank_mask:0xf
	v_cndmask_b32_e64 v89, v201, v97, s[40:41]
	v_pk_mul_f32 v[82:83], v[124:125], v[82:83]
	v_pk_fma_f32 v[78:79], v[78:79], v[130:131], v[84:85]
	v_mov_b32_dpp v121, v76 row_ror:1 row_mask:0xf bank_mask:0xf
	v_mov_b32_dpp v156, v77 row_ror:1 row_mask:0xf bank_mask:0xf
	v_cndmask_b32_e64 v87, v209, v155, s[40:41]
	v_cndmask_b32_e64 v86, v208, v154, s[40:41]
	v_pk_fma_f32 v[80:81], v[80:81], v[132:133], v[82:83]
	v_pk_fma_f32 v[78:79], v[126:127], v[88:89], v[78:79]
	v_mov_b32_dpp v112, v74 row_ror:1 row_mask:0xf bank_mask:0xf
	v_mov_b32_dpp v113, v75 row_ror:1 row_mask:0xf bank_mask:0xf
	v_cndmask_b32_e64 v83, v156, v161, s[42:43]
	v_cndmask_b32_e64 v82, v121, v160, s[42:43]
	v_pk_fma_f32 v[80:81], v[128:129], v[86:87], v[80:81]
	v_pk_add_f32 v[78:79], v[134:135], v[78:79]
	v_cndmask_b32_e64 v85, v113, v159, s[42:43]
	v_cndmask_b32_e64 v84, v112, v158, s[42:43]
	v_pk_mul_f32 v[82:83], v[140:141], v[82:83]
	v_pk_add_f32 v[80:81], v[136:137], v[80:81]
	v_pk_mul_f32 v[84:85], v[138:139], v[84:85]
	v_pk_fma_f32 v[76:77], v[76:77], v[144:145], v[82:83]
	v_mul_f32_e32 v82, 0xbfb8aa3b, v78
	v_mul_f32_e32 v83, 0xbfb8aa3b, v79
	v_pk_fma_f32 v[74:75], v[74:75], v[142:143], v[84:85]
	v_exp_f32_e32 v82, v82
	v_exp_f32_e32 v83, v83
	v_mul_f32_e32 v84, 0xbfb8aa3b, v80
	v_mul_f32_e32 v85, 0xbfb8aa3b, v81
	v_exp_f32_e32 v84, v84
	v_exp_f32_e32 v85, v85
	v_add_f32_e32 v82, 1.0, v82
	v_add_f32_e32 v83, 1.0, v83
	v_rcp_f32_e32 v82, v82
	v_rcp_f32_e32 v83, v83
	v_add_f32_e32 v84, 1.0, v84
	v_add_f32_e32 v85, 1.0, v85
	v_mov_b32_dpp v157, v66 row_ror:15 row_mask:0xf bank_mask:0xf
	v_mov_b32_dpp v197, v67 row_ror:15 row_mask:0xf bank_mask:0xf
	v_rcp_f32_e32 v84, v84
	v_rcp_f32_e32 v85, v85
	v_mov_b32_dpp v198, v68 row_ror:15 row_mask:0xf bank_mask:0xf
	v_mov_b32_dpp v199, v69 row_ror:15 row_mask:0xf bank_mask:0xf
	v_cndmask_b32_e64 v89, v177, v197, s[40:41]
	v_cndmask_b32_e64 v88, v176, v157, s[40:41]
	v_cndmask_b32_e64 v87, v196, v199, s[40:41]
	v_cndmask_b32_e64 v86, v195, v198, s[40:41]
	v_pk_fma_f32 v[74:75], v[146:147], v[88:89], v[74:75]
	v_pk_fma_f32 v[76:77], v[148:149], v[86:87], v[76:77]
	v_pk_add_f32 v[74:75], v[150:151], v[74:75]
	v_pk_mul_f32 v[78:79], v[78:79], v[82:83]
	v_pk_add_f32 v[76:77], v[152:153], v[76:77]
	v_pk_mul_f32 v[74:75], v[78:79], v[74:75]
	v_pk_mul_f32 v[78:79], v[80:81], v[84:85]
	v_cvt_pk_bf16_f32 v74, v74, v75
	v_pk_mul_f32 v[76:77], v[78:79], v[76:77]
	v_cndmask_b32_e64 v81, v97, v99, s[40:41]
	v_cvt_pk_bf16_f32 v75, v76, v77
	v_add_u32_e32 v76, 0xa0, v194
	v_mad_i64_i32 v[76:77], s[22:23], v76, s15, v[90:91]
	v_lshl_add_u64 v[76:77], v[76:77], 0, s[0:1]
	v_lshl_add_u64 v[110:111], v[76:77], 0, v[174:175]
	global_store_dwordx2 v[110:111], v[74:75], off
	v_mov_b32_dpp v74, v72 row_ror:1 row_mask:0xf bank_mask:0xf
	v_mov_b32_dpp v75, v73 row_ror:1 row_mask:0xf bank_mask:0xf
	v_mov_b32_dpp v76, v70 row_ror:1 row_mask:0xf bank_mask:0xf
	v_mov_b32_dpp v77, v71 row_ror:1 row_mask:0xf bank_mask:0xf
	v_cndmask_b32_e64 v75, v75, v95, s[42:43]
	v_cndmask_b32_e64 v74, v74, v94, s[42:43]
	v_cndmask_b32_e64 v77, v77, v93, s[42:43]
	v_cndmask_b32_e64 v76, v76, v92, s[42:43]
	v_pk_mul_f32 v[74:75], v[124:125], v[74:75]
	v_pk_mul_f32 v[76:77], v[122:123], v[76:77]
	v_pk_fma_f32 v[72:73], v[72:73], v[132:133], v[74:75]
	v_cndmask_b32_e64 v80, v96, v98, s[40:41]
	v_pk_fma_f32 v[70:71], v[70:71], v[130:131], v[76:77]
	v_mov_b32_dpp v74, v68 row_ror:1 row_mask:0xf bank_mask:0xf
	v_mov_b32_dpp v75, v69 row_ror:1 row_mask:0xf bank_mask:0xf
	v_cndmask_b32_e64 v79, v155, v101, s[40:41]
	v_cndmask_b32_e64 v78, v154, v100, s[40:41]
	v_pk_fma_f32 v[70:71], v[126:127], v[80:81], v[70:71]
	v_mov_b32_dpp v76, v66 row_ror:1 row_mask:0xf bank_mask:0xf
	v_mov_b32_dpp v77, v67 row_ror:1 row_mask:0xf bank_mask:0xf
	v_cndmask_b32_e64 v75, v75, v156, s[42:43]
	v_cndmask_b32_e64 v74, v74, v121, s[42:43]
	v_pk_fma_f32 v[72:73], v[128:129], v[78:79], v[72:73]
	v_pk_add_f32 v[70:71], v[134:135], v[70:71]
	v_cndmask_b32_e64 v77, v77, v113, s[42:43]
	v_cndmask_b32_e64 v76, v76, v112, s[42:43]
	v_pk_mul_f32 v[74:75], v[140:141], v[74:75]
	v_pk_add_f32 v[72:73], v[136:137], v[72:73]
	v_pk_mul_f32 v[76:77], v[138:139], v[76:77]
	v_pk_fma_f32 v[68:69], v[68:69], v[144:145], v[74:75]
	v_mul_f32_e32 v74, 0xbfb8aa3b, v70
	v_mul_f32_e32 v75, 0xbfb8aa3b, v71
	v_pk_fma_f32 v[66:67], v[66:67], v[142:143], v[76:77]
	v_exp_f32_e32 v74, v74
	v_exp_f32_e32 v75, v75
	v_mul_f32_e32 v76, 0xbfb8aa3b, v72
	v_mul_f32_e32 v77, 0xbfb8aa3b, v73
	v_exp_f32_e32 v76, v76
	v_exp_f32_e32 v77, v77
	v_add_f32_e32 v74, 1.0, v74
	v_add_f32_e32 v75, 1.0, v75
	v_rcp_f32_e32 v74, v74
	v_rcp_f32_e32 v75, v75
	v_add_f32_e32 v76, 1.0, v76
	v_add_f32_e32 v77, 1.0, v77
	v_rcp_f32_e32 v76, v76
	v_rcp_f32_e32 v77, v77
	v_cndmask_b32_e64 v81, v197, v103, s[40:41]
	v_cndmask_b32_e64 v80, v157, v102, s[40:41]
	v_cndmask_b32_e64 v79, v199, v105, s[40:41]
	v_cndmask_b32_e64 v78, v198, v104, s[40:41]
	v_pk_fma_f32 v[66:67], v[146:147], v[80:81], v[66:67]
	v_pk_fma_f32 v[68:69], v[148:149], v[78:79], v[68:69]
	v_pk_add_f32 v[66:67], v[150:151], v[66:67]
	v_pk_mul_f32 v[70:71], v[70:71], v[74:75]
	v_pk_add_f32 v[68:69], v[152:153], v[68:69]
	v_pk_mul_f32 v[66:67], v[66:67], v[70:71]
	v_pk_mul_f32 v[70:71], v[72:73], v[76:77]
	v_cvt_pk_bf16_f32 v66, v66, v67
	v_pk_mul_f32 v[68:69], v[68:69], v[70:71]
	s_and_b64 vcc, exec, s[44:45]
	v_cvt_pk_bf16_f32 v67, v68, v69
	v_add_u32_e32 v68, 0xb0, v194
	v_mad_i64_i32 v[68:69], s[22:23], v68, s15, v[90:91]
	v_lshl_add_u64 v[68:69], v[68:69], 0, s[0:1]
	v_lshl_add_u64 v[98:99], v[68:69], 0, v[174:175]
	global_store_dwordx2 v[98:99], v[66:67], off
	v_mov_b32_e32 v90, 0
	v_mov_b32_e32 v66, 0
	v_mov_b32_e32 v67, 0
	v_mov_b32_e32 v68, 0
	v_mov_b32_e32 v69, 0
	s_cbranch_vccnz .LBB0_115
	ds_read_b128 v[66:69], v192 offset:16

.LBB0_121:
	v_mov_b32_dpp v104, v62 row_ror:1 row_mask:0xf bank_mask:0xf
	v_mov_b32_dpp v105, v63 row_ror:1 row_mask:0xf bank_mask:0xf
	v_mov_b32_dpp v112, v64 row_ror:1 row_mask:0xf bank_mask:0xf
	v_mov_b32_dpp v113, v65 row_ror:1 row_mask:0xf bank_mask:0xf
	v_mov_b32_dpp v74, v62 row_ror:15 row_mask:0xf bank_mask:0xf
	v_mov_b32_dpp v75, v63 row_ror:15 row_mask:0xf bank_mask:0xf
	v_mov_b32_dpp v76, v64 row_ror:15 row_mask:0xf bank_mask:0xf
	v_mov_b32_dpp v77, v65 row_ror:15 row_mask:0xf bank_mask:0xf
	v_mov_b32_dpp v121, v54 row_ror:15 row_mask:0xf bank_mask:0xf
	v_mov_b32_dpp v122, v55 row_ror:15 row_mask:0xf bank_mask:0xf
	v_mov_b32_dpp v124, v56 row_ror:15 row_mask:0xf bank_mask:0xf
	v_mov_b32_dpp v126, v57 row_ror:15 row_mask:0xf bank_mask:0xf
	s_waitcnt lgkmcnt(0)
	v_cndmask_b32_e64 v71, v105, v67, s[42:43]
	v_cndmask_b32_e64 v70, v104, v66, s[42:43]
	v_cndmask_b32_e64 v73, v113, v69, s[42:43]
	v_cndmask_b32_e64 v72, v112, v68, s[42:43]
	v_cndmask_b32_e64 v83, v75, v122, s[40:41]
	v_cndmask_b32_e64 v82, v74, v121, s[40:41]
	v_cndmask_b32_e64 v85, v77, v126, s[40:41]
	v_cndmask_b32_e64 v84, v76, v124, s[40:41]
	ds_read_b128 v[66:69], v190 offset:16
	ds_read_b128 v[74:77], v190 offset:1040
	s_waitcnt lgkmcnt(0)
	v_pk_mul_f32 v[64:65], v[64:65], v[76:77]
	v_pk_mul_f32 v[62:63], v[62:63], v[74:75]
	v_pk_fma_f32 v[72:73], v[72:73], v[68:69], v[64:65]
	v_pk_fma_f32 v[70:71], v[70:71], v[66:67], v[62:63]
	ds_read_b128 v[62:65], v190 offset:2064
	s_waitcnt lgkmcnt(0)
	v_pk_fma_f32 v[84:85], v[64:65], v[84:85], v[72:73]
	v_pk_fma_f32 v[82:83], v[62:63], v[82:83], v[70:71]
	ds_read_b128 v[70:73], v190 offset:3088
	v_mov_b32_dpp v123, v58 row_ror:1 row_mask:0xf bank_mask:0xf
	v_mov_b32_dpp v125, v59 row_ror:1 row_mask:0xf bank_mask:0xf
	v_mov_b32_dpp v127, v60 row_ror:1 row_mask:0xf bank_mask:0xf
	v_mov_b32_dpp v128, v61 row_ror:1 row_mask:0xf bank_mask:0xf
	s_waitcnt lgkmcnt(0)
	v_pk_add_f32 v[100:101], v[72:73], v[84:85]
	v_pk_add_f32 v[102:103], v[70:71], v[82:83]
	v_mov_b32_dpp v82, v58 row_ror:15 row_mask:0xf bank_mask:0xf
	v_mov_b32_dpp v83, v59 row_ror:15 row_mask:0xf bank_mask:0xf
	v_mov_b32_dpp v84, v60 row_ror:15 row_mask:0xf bank_mask:0xf
	v_mov_b32_dpp v85, v61 row_ror:15 row_mask:0xf bank_mask:0xf
	v_mov_b32_dpp v129, v50 row_ror:15 row_mask:0xf bank_mask:0xf
	v_mov_b32_dpp v130, v51 row_ror:15 row_mask:0xf bank_mask:0xf
	v_mov_b32_dpp v131, v52 row_ror:15 row_mask:0xf bank_mask:0xf
	v_mov_b32_dpp v132, v53 row_ror:15 row_mask:0xf bank_mask:0xf
	v_cndmask_b32_e64 v87, v125, v79, s[42:43]
	v_cndmask_b32_e64 v86, v123, v78, s[42:43]
	v_cndmask_b32_e64 v89, v128, v81, s[42:43]
	v_cndmask_b32_e64 v88, v127, v80, s[42:43]
	v_cndmask_b32_e64 v135, v83, v130, s[40:41]
	v_cndmask_b32_e64 v134, v82, v129, s[40:41]
	v_cndmask_b32_e64 v137, v85, v132, s[40:41]
	v_cndmask_b32_e64 v136, v84, v131, s[40:41]
	ds_read_b128 v[78:81], v190 offset:528
	ds_read_b128 v[82:85], v190 offset:1552
	v_mul_f32_e32 v133, 0xbfb8aa3b, v102
	v_exp_f32_e32 v133, v133
	s_waitcnt lgkmcnt(0)
	v_pk_mul_f32 v[60:61], v[60:61], v[84:85]
	v_pk_mul_f32 v[58:59], v[58:59], v[82:83]
	v_add_f32_e32 v133, 1.0, v133
	v_pk_fma_f32 v[88:89], v[88:89], v[80:81], v[60:61]
	v_pk_fma_f32 v[86:87], v[86:87], v[78:79], v[58:59]
	ds_read_b128 v[58:61], v190 offset:2576
	v_rcp_f32_e32 v138, v133
	v_mul_f32_e32 v133, 0xbfb8aa3b, v103
	v_exp_f32_e32 v133, v133
	v_mov_b32_dpp v140, v49 row_ror:15 row_mask:0xf bank_mask:0xf
	s_waitcnt lgkmcnt(0)
	v_pk_fma_f32 v[136:137], v[60:61], v[136:137], v[88:89]
	v_pk_fma_f32 v[134:135], v[58:59], v[134:135], v[86:87]
	ds_read_b128 v[86:89], v190 offset:3600
	v_add_f32_e32 v133, 1.0, v133
	v_rcp_f32_e32 v139, v133
	s_waitcnt lgkmcnt(0)
	v_pk_add_f32 v[134:135], v[86:87], v[134:135]
	v_pk_mul_f32 v[102:103], v[102:103], v[138:139]
	v_pk_add_f32 v[136:137], v[88:89], v[136:137]
	v_pk_mul_f32 v[102:103], v[102:103], v[134:135]
	v_mov_b32_dpp v133, v54 row_ror:1 row_mask:0xf bank_mask:0xf
	v_cvt_pk_bf16_f32 v102, v102, v103
	v_mul_f32_e32 v103, 0xbfb8aa3b, v100
	v_exp_f32_e32 v103, v103
	v_mov_b32_dpp v141, v42 row_ror:15 row_mask:0xf bank_mask:0xf
	v_add_f32_e32 v103, 1.0, v103
	v_rcp_f32_e32 v134, v103
	v_mul_f32_e32 v103, 0xbfb8aa3b, v101
	v_exp_f32_e32 v103, v103
	v_mov_b32_dpp v139, v48 row_ror:15 row_mask:0xf bank_mask:0xf
	v_mov_b32_dpp v138, v47 row_ror:15 row_mask:0xf bank_mask:0xf
	v_mov_b32_dpp v142, v43 row_ror:15 row_mask:0xf bank_mask:0xf
	v_add_f32_e32 v103, 1.0, v103
	v_rcp_f32_e32 v135, v103
	s_and_b64 vcc, exec, s[48:49]
	v_pk_mul_f32 v[100:101], v[100:101], v[134:135]
	v_pk_mul_f32 v[100:101], v[100:101], v[136:137]
	v_cvt_pk_bf16_f32 v103, v100, v101
	v_mov_b32_dpp v134, v55 row_ror:1 row_mask:0xf bank_mask:0xf
	global_store_dwordx2 v[172:173], v[102:103], off offset:8
	v_mov_b32_dpp v135, v56 row_ror:1 row_mask:0xf bank_mask:0xf
	v_mov_b32_dpp v136, v57 row_ror:1 row_mask:0xf bank_mask:0xf
	v_cndmask_b32_e64 v103, v134, v105, s[42:43]
	v_cndmask_b32_e64 v102, v133, v104, s[42:43]
	v_mov_b32_dpp v137, v46 row_ror:15 row_mask:0xf bank_mask:0xf
	v_cndmask_b32_e64 v101, v136, v113, s[42:43]
	v_cndmask_b32_e64 v100, v135, v112, s[42:43]
	v_cndmask_b32_e64 v105, v126, v140, s[40:41]
	v_cndmask_b32_e64 v104, v124, v139, s[40:41]
	v_pk_mul_f32 v[102:103], v[66:67], v[102:103]
	v_cndmask_b32_e64 v113, v122, v138, s[40:41]
	v_cndmask_b32_e64 v112, v121, v137, s[40:41]
	v_pk_mul_f32 v[100:101], v[68:69], v[100:101]
	v_pk_fma_f32 v[54:55], v[54:55], v[74:75], v[102:103]
	v_mov_b32_dpp v124, v52 row_ror:1 row_mask:0xf bank_mask:0xf
	v_mov_b32_dpp v126, v53 row_ror:1 row_mask:0xf bank_mask:0xf
	v_pk_fma_f32 v[56:57], v[56:57], v[76:77], v[100:101]
	v_pk_fma_f32 v[54:55], v[62:63], v[112:113], v[54:55]
	v_cndmask_b32_e64 v101, v126, v128, s[42:43]
	v_cndmask_b32_e64 v100, v124, v127, s[42:43]
	v_pk_add_f32 v[54:55], v[70:71], v[54:55]
	v_pk_mul_f32 v[100:101], v[80:81], v[100:101]
	v_pk_fma_f32 v[52:53], v[52:53], v[84:85], v[100:101]
	v_mul_f32_e32 v100, 0xbfb8aa3b, v54
	v_mul_f32_e32 v101, 0xbfb8aa3b, v55
	v_exp_f32_e32 v100, v100
	v_exp_f32_e32 v101, v101
	v_mov_b32_dpp v121, v50 row_ror:1 row_mask:0xf bank_mask:0xf
	v_add_f32_e32 v100, 1.0, v100
	v_mov_b32_dpp v122, v51 row_ror:1 row_mask:0xf bank_mask:0xf
	v_add_f32_e32 v101, 1.0, v101
	v_cndmask_b32_e64 v103, v122, v125, s[42:43]
	v_cndmask_b32_e64 v102, v121, v123, s[42:43]
	v_rcp_f32_e32 v100, v100
	v_rcp_f32_e32 v101, v101
	v_pk_mul_f32 v[102:103], v[78:79], v[102:103]
	v_cndmask_b32_e64 v113, v130, v142, s[40:41]
	v_cndmask_b32_e64 v112, v129, v141, s[40:41]
	v_pk_fma_f32 v[50:51], v[50:51], v[82:83], v[102:103]
	v_pk_fma_f32 v[56:57], v[64:65], v[104:105], v[56:57]
	v_pk_fma_f32 v[50:51], v[58:59], v[112:113], v[50:51]
	v_pk_mul_f32 v[54:55], v[54:55], v[100:101]
	v_pk_add_f32 v[50:51], v[86:87], v[50:51]
	v_pk_add_f32 v[56:57], v[72:73], v[56:57]
	v_pk_mul_f32 v[50:51], v[54:55], v[50:51]
	v_mov_b32_dpp v143, v44 row_ror:15 row_mask:0xf bank_mask:0xf
	v_cvt_pk_bf16_f32 v50, v50, v51
	v_mul_f32_e32 v51, 0xbfb8aa3b, v56
	v_exp_f32_e32 v51, v51
	v_mov_b32_dpp v144, v45 row_ror:15 row_mask:0xf bank_mask:0xf
	v_cndmask_b32_e64 v105, v132, v144, s[40:41]
	v_cndmask_b32_e64 v104, v131, v143, s[40:41]
	v_add_f32_e32 v51, 1.0, v51
	v_rcp_f32_e32 v54, v51
	v_mul_f32_e32 v51, 0xbfb8aa3b, v57
	v_exp_f32_e32 v51, v51
	v_pk_fma_f32 v[52:53], v[60:61], v[104:105], v[52:53]
	v_pk_add_f32 v[52:53], v[88:89], v[52:53]
	v_add_f32_e32 v51, 1.0, v51
	v_rcp_f32_e32 v55, v51
	v_mov_b32_dpp v100, v46 row_ror:1 row_mask:0xf bank_mask:0xf
	v_pk_mul_f32 v[54:55], v[56:57], v[54:55]
	v_mov_b32_dpp v101, v47 row_ror:1 row_mask:0xf bank_mask:0xf
	v_pk_mul_f32 v[52:53], v[54:55], v[52:53]
	v_cvt_pk_bf16_f32 v51, v52, v53
	v_mov_b32_dpp v102, v48 row_ror:1 row_mask:0xf bank_mask:0xf
	v_mov_b32_dpp v103, v49 row_ror:1 row_mask:0xf bank_mask:0xf
	v_cndmask_b32_e64 v53, v101, v134, s[42:43]
	v_cndmask_b32_e64 v52, v100, v133, s[42:43]
	global_store_dwordx2 v[114:115], v[50:51], off offset:8
	v_mov_b32_dpp v104, v38 row_ror:15 row_mask:0xf bank_mask:0xf
	v_mov_b32_dpp v105, v39 row_ror:15 row_mask:0xf bank_mask:0xf
	v_cndmask_b32_e64 v51, v103, v136, s[42:43]
	v_cndmask_b32_e64 v50, v102, v135, s[42:43]
	v_pk_mul_f32 v[52:53], v[66:67], v[52:53]
	v_cndmask_b32_e64 v57, v138, v105, s[40:41]
	v_cndmask_b32_e64 v56, v137, v104, s[40:41]
	v_pk_mul_f32 v[50:51], v[68:69], v[50:51]
	v_pk_fma_f32 v[46:47], v[46:47], v[74:75], v[52:53]
	v_mov_b32_dpp v123, v44 row_ror:1 row_mask:0xf bank_mask:0xf
	v_mov_b32_dpp v125, v45 row_ror:1 row_mask:0xf bank_mask:0xf
	v_pk_fma_f32 v[48:49], v[48:49], v[76:77], v[50:51]
	v_pk_fma_f32 v[46:47], v[62:63], v[56:57], v[46:47]
	v_cndmask_b32_e64 v51, v125, v126, s[42:43]
	v_cndmask_b32_e64 v50, v123, v124, s[42:43]
	v_pk_add_f32 v[46:47], v[70:71], v[46:47]
	v_pk_mul_f32 v[50:51], v[80:81], v[50:51]
	v_pk_fma_f32 v[44:45], v[44:45], v[84:85], v[50:51]
	v_mul_f32_e32 v50, 0xbfb8aa3b, v46
	v_mul_f32_e32 v51, 0xbfb8aa3b, v47
	v_exp_f32_e32 v50, v50
	v_exp_f32_e32 v51, v51
	v_mov_b32_dpp v114, v42 row_ror:1 row_mask:0xf bank_mask:0xf
	v_add_f32_e32 v50, 1.0, v50
	v_mov_b32_dpp v115, v43 row_ror:1 row_mask:0xf bank_mask:0xf
	v_add_f32_e32 v51, 1.0, v51
	v_cndmask_b32_e64 v53, v115, v122, s[42:43]
	v_cndmask_b32_e64 v52, v114, v121, s[42:43]
	v_rcp_f32_e32 v50, v50
	v_rcp_f32_e32 v51, v51
	v_mov_b32_dpp v127, v34 row_ror:15 row_mask:0xf bank_mask:0xf
	v_mov_b32_dpp v128, v35 row_ror:15 row_mask:0xf bank_mask:0xf
	v_pk_mul_f32 v[52:53], v[78:79], v[52:53]
	v_mov_b32_dpp v112, v40 row_ror:15 row_mask:0xf bank_mask:0xf
	v_mov_b32_dpp v113, v41 row_ror:15 row_mask:0xf bank_mask:0xf
	v_cndmask_b32_e64 v57, v142, v128, s[40:41]
	v_cndmask_b32_e64 v56, v141, v127, s[40:41]
	v_pk_fma_f32 v[42:43], v[42:43], v[82:83], v[52:53]
	v_cndmask_b32_e64 v55, v140, v113, s[40:41]
	v_cndmask_b32_e64 v54, v139, v112, s[40:41]
	v_pk_fma_f32 v[42:43], v[58:59], v[56:57], v[42:43]
	v_pk_fma_f32 v[48:49], v[64:65], v[54:55], v[48:49]
	v_pk_add_f32 v[42:43], v[86:87], v[42:43]
	v_pk_mul_f32 v[46:47], v[46:47], v[50:51]
	v_pk_add_f32 v[48:49], v[72:73], v[48:49]
	v_pk_mul_f32 v[42:43], v[46:47], v[42:43]
	v_cvt_pk_bf16_f32 v42, v42, v43
	v_mul_f32_e32 v43, 0xbfb8aa3b, v48
	v_exp_f32_e32 v43, v43
	v_mov_b32_dpp v129, v36 row_ror:15 row_mask:0xf bank_mask:0xf
	v_cndmask_b32_e64 v54, v143, v129, s[40:41]
	v_add_f32_e32 v43, 1.0, v43
	v_rcp_f32_e32 v46, v43
	v_mul_f32_e32 v43, 0xbfb8aa3b, v49
	v_exp_f32_e32 v43, v43
	v_mov_b32_dpp v130, v37 row_ror:15 row_mask:0xf bank_mask:0xf
	v_cndmask_b32_e64 v55, v144, v130, s[40:41]
	v_pk_fma_f32 v[44:45], v[60:61], v[54:55], v[44:45]
	v_add_f32_e32 v43, 1.0, v43
	v_rcp_f32_e32 v47, v43
	v_pk_add_f32 v[44:45], v[88:89], v[44:45]
	v_pk_mul_f32 v[46:47], v[48:49], v[46:47]
	s_nop 0
	v_pk_mul_f32 v[44:45], v[46:47], v[44:45]
	v_cndmask_b32_e64 v49, v105, v91, s[40:41]
	v_cvt_pk_bf16_f32 v43, v44, v45
	global_store_dwordx2 v[116:117], v[42:43], off offset:8
	v_mov_b32_dpp v42, v40 row_ror:1 row_mask:0xf bank_mask:0xf
	v_mov_b32_dpp v43, v41 row_ror:1 row_mask:0xf bank_mask:0xf
	v_mov_b32_dpp v44, v38 row_ror:1 row_mask:0xf bank_mask:0xf
	v_mov_b32_dpp v45, v39 row_ror:1 row_mask:0xf bank_mask:0xf
	v_cndmask_b32_e64 v43, v43, v103, s[42:43]
	v_cndmask_b32_e64 v42, v42, v102, s[42:43]
	v_cndmask_b32_e64 v45, v45, v101, s[42:43]
	v_cndmask_b32_e64 v44, v44, v100, s[42:43]
	v_pk_mul_f32 v[42:43], v[68:69], v[42:43]
	v_pk_mul_f32 v[44:45], v[66:67], v[44:45]
	v_pk_fma_f32 v[40:41], v[40:41], v[76:77], v[42:43]
	v_cndmask_b32_e64 v48, v104, v90, s[40:41]
	v_pk_fma_f32 v[38:39], v[38:39], v[74:75], v[44:45]
	v_mov_b32_dpp v42, v36 row_ror:1 row_mask:0xf bank_mask:0xf
	v_mov_b32_dpp v43, v37 row_ror:1 row_mask:0xf bank_mask:0xf
	v_pk_fma_f32 v[38:39], v[62:63], v[48:49], v[38:39]
	v_cndmask_b32_e64 v43, v43, v125, s[42:43]
	v_cndmask_b32_e64 v42, v42, v123, s[42:43]
	v_pk_add_f32 v[38:39], v[70:71], v[38:39]
	v_pk_mul_f32 v[42:43], v[80:81], v[42:43]
	v_pk_fma_f32 v[36:37], v[36:37], v[84:85], v[42:43]
	v_mul_f32_e32 v42, 0xbfb8aa3b, v38
	v_mul_f32_e32 v43, 0xbfb8aa3b, v39
	v_exp_f32_e32 v42, v42
	v_exp_f32_e32 v43, v43
	v_mov_b32_dpp v44, v34 row_ror:1 row_mask:0xf bank_mask:0xf
	v_add_f32_e32 v42, 1.0, v42
	v_mov_b32_dpp v45, v35 row_ror:1 row_mask:0xf bank_mask:0xf
	v_add_f32_e32 v43, 1.0, v43
	v_cndmask_b32_e64 v45, v45, v115, s[42:43]
	v_cndmask_b32_e64 v44, v44, v114, s[42:43]
	v_rcp_f32_e32 v42, v42
	v_rcp_f32_e32 v43, v43
	v_pk_mul_f32 v[44:45], v[78:79], v[44:45]
	v_cndmask_b32_e64 v49, v128, v95, s[40:41]
	v_cndmask_b32_e64 v48, v127, v94, s[40:41]
	v_pk_fma_f32 v[34:35], v[34:35], v[82:83], v[44:45]
	v_cndmask_b32_e64 v47, v113, v93, s[40:41]
	v_cndmask_b32_e64 v46, v112, v92, s[40:41]
	v_pk_fma_f32 v[34:35], v[58:59], v[48:49], v[34:35]
	v_pk_fma_f32 v[40:41], v[64:65], v[46:47], v[40:41]
	v_pk_add_f32 v[34:35], v[86:87], v[34:35]
	v_pk_mul_f32 v[38:39], v[38:39], v[42:43]
	v_pk_add_f32 v[40:41], v[72:73], v[40:41]
	v_pk_mul_f32 v[34:35], v[34:35], v[38:39]
	v_cndmask_b32_e64 v47, v130, v97, s[40:41]
	v_cvt_pk_bf16_f32 v34, v34, v35
	v_mul_f32_e32 v35, 0xbfb8aa3b, v40
	v_exp_f32_e32 v35, v35
	v_cndmask_b32_e64 v46, v129, v96, s[40:41]
	v_pk_fma_f32 v[36:37], v[60:61], v[46:47], v[36:37]
	v_mov_b32_e32 v46, 0
	v_add_f32_e32 v35, 1.0, v35
	v_rcp_f32_e32 v38, v35
	v_mul_f32_e32 v35, 0xbfb8aa3b, v41
	v_exp_f32_e32 v35, v35
	v_pk_add_f32 v[36:37], v[88:89], v[36:37]
	v_mov_b32_e32 v47, 0
	v_mov_b32_e32 v48, 0
	v_add_f32_e32 v35, 1.0, v35
	v_rcp_f32_e32 v39, v35
	v_mov_b32_e32 v49, 0
	v_pk_mul_f32 v[38:39], v[40:41], v[38:39]
	s_nop 0
	v_pk_mul_f32 v[36:37], v[36:37], v[38:39]
	s_nop 0
	v_cvt_pk_bf16_f32 v35, v36, v37
	global_store_dwordx2 v[118:119], v[34:35], off offset:8
	v_mov_b32_e32 v34, 0
	s_cbranch_vccnz .LBB0_123
	ds_read_b128 v[46:49], v120 offset:16

.LBB0_129:
	v_mov_b32_dpp v56, v32 row_ror:1 row_mask:0xf bank_mask:0xf
	v_mov_b32_dpp v57, v33 row_ror:1 row_mask:0xf bank_mask:0xf
	v_mov_b32_dpp v54, v30 row_ror:1 row_mask:0xf bank_mask:0xf
	v_mov_b32_dpp v55, v31 row_ror:1 row_mask:0xf bank_mask:0xf
	s_waitcnt lgkmcnt(0)
	v_cndmask_b32_e64 v49, v57, v49, s[42:43]
	v_cndmask_b32_e64 v48, v56, v48, s[42:43]
	v_mov_b32_dpp v50, v32 row_ror:15 row_mask:0xf bank_mask:0xf
	v_mov_b32_dpp v51, v33 row_ror:15 row_mask:0xf bank_mask:0xf
	v_mov_b32_dpp v92, v24 row_ror:15 row_mask:0xf bank_mask:0xf
	v_mov_b32_dpp v93, v25 row_ror:15 row_mask:0xf bank_mask:0xf
	v_cndmask_b32_e64 v47, v55, v47, s[42:43]
	v_cndmask_b32_e64 v46, v54, v46, s[42:43]
	v_pk_mul_f32 v[48:49], v[68:69], v[48:49]
	v_mov_b32_dpp v52, v30 row_ror:15 row_mask:0xf bank_mask:0xf
	v_mov_b32_dpp v53, v31 row_ror:15 row_mask:0xf bank_mask:0xf
	v_mov_b32_dpp v90, v22 row_ror:15 row_mask:0xf bank_mask:0xf
	v_mov_b32_dpp v91, v23 row_ror:15 row_mask:0xf bank_mask:0xf
	v_cndmask_b32_e64 v51, v51, v93, s[40:41]
	v_cndmask_b32_e64 v50, v50, v92, s[40:41]
	v_pk_mul_f32 v[46:47], v[66:67], v[46:47]
	v_pk_fma_f32 v[32:33], v[32:33], v[76:77], v[48:49]
	v_cndmask_b32_e64 v53, v53, v91, s[40:41]
	v_cndmask_b32_e64 v52, v52, v90, s[40:41]
	v_pk_fma_f32 v[30:31], v[30:31], v[74:75], v[46:47]
	v_pk_fma_f32 v[32:33], v[64:65], v[50:51], v[32:33]
	v_pk_fma_f32 v[30:31], v[62:63], v[52:53], v[30:31]
	v_mov_b32_dpp v50, v26 row_ror:1 row_mask:0xf bank_mask:0xf
	v_mov_b32_dpp v51, v27 row_ror:1 row_mask:0xf bank_mask:0xf
	v_cndmask_b32_e64 v43, v51, v43, s[42:43]
	v_mov_b32_dpp v52, v28 row_ror:1 row_mask:0xf bank_mask:0xf
	v_mov_b32_dpp v53, v29 row_ror:1 row_mask:0xf bank_mask:0xf
	v_cndmask_b32_e64 v42, v50, v42, s[42:43]
	v_pk_add_f32 v[30:31], v[70:71], v[30:31]
	v_cndmask_b32_e64 v45, v53, v45, s[42:43]
	v_cndmask_b32_e64 v44, v52, v44, s[42:43]
	v_pk_mul_f32 v[42:43], v[78:79], v[42:43]
	v_pk_add_f32 v[32:33], v[72:73], v[32:33]
	v_mov_b32_dpp v48, v26 row_ror:15 row_mask:0xf bank_mask:0xf
	v_mov_b32_dpp v49, v27 row_ror:15 row_mask:0xf bank_mask:0xf
	v_pk_mul_f32 v[44:45], v[80:81], v[44:45]
	v_pk_fma_f32 v[26:27], v[26:27], v[82:83], v[42:43]
	v_mul_f32_e32 v42, 0xbfb8aa3b, v30
	v_mul_f32_e32 v43, 0xbfb8aa3b, v31
	v_mov_b32_dpp v46, v28 row_ror:15 row_mask:0xf bank_mask:0xf
	v_mov_b32_dpp v47, v29 row_ror:15 row_mask:0xf bank_mask:0xf
	v_pk_fma_f32 v[28:29], v[28:29], v[84:85], v[44:45]
	v_exp_f32_e32 v42, v42
	v_exp_f32_e32 v43, v43
	v_mul_f32_e32 v44, 0xbfb8aa3b, v32
	v_mul_f32_e32 v45, 0xbfb8aa3b, v33
	v_exp_f32_e32 v44, v44
	v_exp_f32_e32 v45, v45
	v_add_f32_e32 v42, 1.0, v42
	v_add_f32_e32 v43, 1.0, v43
	v_rcp_f32_e32 v42, v42
	v_rcp_f32_e32 v43, v43
	v_add_f32_e32 v44, 1.0, v44
	v_add_f32_e32 v45, 1.0, v45
	v_mov_b32_dpp v94, v18 row_ror:15 row_mask:0xf bank_mask:0xf
	v_mov_b32_dpp v95, v19 row_ror:15 row_mask:0xf bank_mask:0xf
	v_rcp_f32_e32 v44, v44
	v_rcp_f32_e32 v45, v45
	v_mov_b32_dpp v96, v20 row_ror:15 row_mask:0xf bank_mask:0xf
	v_mov_b32_dpp v97, v21 row_ror:15 row_mask:0xf bank_mask:0xf
	v_cndmask_b32_e64 v49, v49, v95, s[40:41]
	v_cndmask_b32_e64 v48, v48, v94, s[40:41]
	v_cndmask_b32_e64 v47, v47, v97, s[40:41]
	v_cndmask_b32_e64 v46, v46, v96, s[40:41]
	v_pk_fma_f32 v[26:27], v[58:59], v[48:49], v[26:27]
	v_pk_fma_f32 v[28:29], v[60:61], v[46:47], v[28:29]
	v_pk_add_f32 v[26:27], v[86:87], v[26:27]
	v_pk_mul_f32 v[30:31], v[30:31], v[42:43]
	v_pk_add_f32 v[28:29], v[88:89], v[28:29]
	v_pk_mul_f32 v[26:27], v[30:31], v[26:27]
	v_pk_mul_f32 v[30:31], v[32:33], v[44:45]
	v_pk_mul_f32 v[28:29], v[30:31], v[28:29]
	v_mov_b32_dpp v42, v22 row_ror:1 row_mask:0xf bank_mask:0xf
	v_mov_b32_dpp v43, v23 row_ror:1 row_mask:0xf bank_mask:0xf
	v_cvt_pk_bf16_f32 v26, v26, v27
	v_cvt_pk_bf16_f32 v27, v28, v29
	v_mov_b32_dpp v44, v24 row_ror:1 row_mask:0xf bank_mask:0xf
	v_mov_b32_dpp v45, v25 row_ror:1 row_mask:0xf bank_mask:0xf
	v_cndmask_b32_e64 v29, v43, v55, s[42:43]
	v_cndmask_b32_e64 v28, v42, v54, s[42:43]
	global_store_dwordx2 v[106:107], v[26:27], off offset:8
	v_mov_b32_dpp v46, v14 row_ror:15 row_mask:0xf bank_mask:0xf
	v_mov_b32_dpp v47, v15 row_ror:15 row_mask:0xf bank_mask:0xf
	v_cndmask_b32_e64 v27, v45, v57, s[42:43]
	v_cndmask_b32_e64 v26, v44, v56, s[42:43]
	v_pk_mul_f32 v[28:29], v[66:67], v[28:29]
	v_mov_b32_dpp v48, v16 row_ror:15 row_mask:0xf bank_mask:0xf
	v_mov_b32_dpp v49, v17 row_ror:15 row_mask:0xf bank_mask:0xf
	v_cndmask_b32_e64 v33, v91, v47, s[40:41]
	v_cndmask_b32_e64 v32, v90, v46, s[40:41]
	v_pk_mul_f32 v[26:27], v[68:69], v[26:27]
	v_pk_fma_f32 v[22:23], v[22:23], v[74:75], v[28:29]
	v_mov_b32_dpp v56, v20 row_ror:1 row_mask:0xf bank_mask:0xf
	v_mov_b32_dpp v57, v21 row_ror:1 row_mask:0xf bank_mask:0xf
	v_cndmask_b32_e64 v31, v93, v49, s[40:41]
	v_cndmask_b32_e64 v30, v92, v48, s[40:41]
	v_pk_fma_f32 v[24:25], v[24:25], v[76:77], v[26:27]
	v_pk_fma_f32 v[22:23], v[62:63], v[32:33], v[22:23]
	v_mov_b32_dpp v54, v18 row_ror:1 row_mask:0xf bank_mask:0xf
	v_mov_b32_dpp v55, v19 row_ror:1 row_mask:0xf bank_mask:0xf
	v_cndmask_b32_e64 v27, v57, v53, s[42:43]
	v_cndmask_b32_e64 v26, v56, v52, s[42:43]
	v_pk_fma_f32 v[24:25], v[64:65], v[30:31], v[24:25]
	v_pk_add_f32 v[22:23], v[70:71], v[22:23]
	v_cndmask_b32_e64 v29, v55, v51, s[42:43]
	v_cndmask_b32_e64 v28, v54, v50, s[42:43]
	v_pk_mul_f32 v[26:27], v[80:81], v[26:27]
	v_pk_add_f32 v[24:25], v[72:73], v[24:25]
	v_pk_mul_f32 v[28:29], v[78:79], v[28:29]
	v_pk_fma_f32 v[20:21], v[20:21], v[84:85], v[26:27]
	v_mul_f32_e32 v26, 0xbfb8aa3b, v22
	v_mul_f32_e32 v27, 0xbfb8aa3b, v23
	v_pk_fma_f32 v[18:19], v[18:19], v[82:83], v[28:29]
	v_exp_f32_e32 v26, v26
	v_exp_f32_e32 v27, v27
	v_mul_f32_e32 v28, 0xbfb8aa3b, v24
	v_mul_f32_e32 v29, 0xbfb8aa3b, v25
	v_exp_f32_e32 v28, v28
	v_exp_f32_e32 v29, v29
	v_add_f32_e32 v26, 1.0, v26
	v_add_f32_e32 v27, 1.0, v27
	v_rcp_f32_e32 v26, v26
	v_rcp_f32_e32 v27, v27
	v_add_f32_e32 v28, 1.0, v28
	v_add_f32_e32 v29, 1.0, v29
	v_mov_b32_dpp v90, v10 row_ror:15 row_mask:0xf bank_mask:0xf
	v_mov_b32_dpp v91, v11 row_ror:15 row_mask:0xf bank_mask:0xf
	v_rcp_f32_e32 v28, v28
	v_rcp_f32_e32 v29, v29
	v_mov_b32_dpp v92, v12 row_ror:15 row_mask:0xf bank_mask:0xf
	v_mov_b32_dpp v93, v13 row_ror:15 row_mask:0xf bank_mask:0xf
	v_cndmask_b32_e64 v33, v95, v91, s[40:41]
	v_cndmask_b32_e64 v32, v94, v90, s[40:41]
	v_cndmask_b32_e64 v31, v97, v93, s[40:41]
	v_cndmask_b32_e64 v30, v96, v92, s[40:41]
	v_pk_fma_f32 v[18:19], v[58:59], v[32:33], v[18:19]
	v_pk_fma_f32 v[20:21], v[60:61], v[30:31], v[20:21]
	v_pk_add_f32 v[18:19], v[86:87], v[18:19]
	v_pk_mul_f32 v[22:23], v[22:23], v[26:27]
	v_pk_add_f32 v[20:21], v[88:89], v[20:21]
	v_pk_mul_f32 v[18:19], v[22:23], v[18:19]
	v_pk_mul_f32 v[22:23], v[24:25], v[28:29]
	v_pk_mul_f32 v[20:21], v[22:23], v[20:21]
	v_mov_b32_dpp v26, v14 row_ror:1 row_mask:0xf bank_mask:0xf
	v_mov_b32_dpp v27, v15 row_ror:1 row_mask:0xf bank_mask:0xf
	v_cvt_pk_bf16_f32 v18, v18, v19
	v_cvt_pk_bf16_f32 v19, v20, v21
	v_mov_b32_dpp v28, v16 row_ror:1 row_mask:0xf bank_mask:0xf
	v_mov_b32_dpp v29, v17 row_ror:1 row_mask:0xf bank_mask:0xf
	v_cndmask_b32_e64 v21, v27, v43, s[42:43]
	v_cndmask_b32_e64 v20, v26, v42, s[42:43]
	global_store_dwordx2 v[108:109], v[18:19], off offset:8
	v_mov_b32_dpp v30, v6 row_ror:15 row_mask:0xf bank_mask:0xf
	v_mov_b32_dpp v31, v7 row_ror:15 row_mask:0xf bank_mask:0xf
	v_cndmask_b32_e64 v19, v29, v45, s[42:43]
	v_cndmask_b32_e64 v18, v28, v44, s[42:43]
	v_pk_mul_f32 v[20:21], v[66:67], v[20:21]
	v_mov_b32_dpp v32, v8 row_ror:15 row_mask:0xf bank_mask:0xf
	v_mov_b32_dpp v33, v9 row_ror:15 row_mask:0xf bank_mask:0xf
	v_cndmask_b32_e64 v25, v47, v31, s[40:41]
	v_cndmask_b32_e64 v24, v46, v30, s[40:41]
	v_pk_mul_f32 v[18:19], v[68:69], v[18:19]
	v_pk_fma_f32 v[14:15], v[14:15], v[74:75], v[20:21]
	v_mov_b32_dpp v44, v12 row_ror:1 row_mask:0xf bank_mask:0xf
	v_mov_b32_dpp v45, v13 row_ror:1 row_mask:0xf bank_mask:0xf
	v_cndmask_b32_e64 v23, v49, v33, s[40:41]
	v_cndmask_b32_e64 v22, v48, v32, s[40:41]
	v_pk_fma_f32 v[16:17], v[16:17], v[76:77], v[18:19]
	v_pk_fma_f32 v[14:15], v[62:63], v[24:25], v[14:15]
	v_mov_b32_dpp v42, v10 row_ror:1 row_mask:0xf bank_mask:0xf
	v_mov_b32_dpp v43, v11 row_ror:1 row_mask:0xf bank_mask:0xf
	v_cndmask_b32_e64 v19, v45, v57, s[42:43]
	v_cndmask_b32_e64 v18, v44, v56, s[42:43]
	v_pk_fma_f32 v[16:17], v[64:65], v[22:23], v[16:17]
	v_pk_add_f32 v[14:15], v[70:71], v[14:15]
	v_cndmask_b32_e64 v21, v43, v55, s[42:43]
	v_cndmask_b32_e64 v20, v42, v54, s[42:43]
	v_pk_mul_f32 v[18:19], v[80:81], v[18:19]
	v_pk_add_f32 v[16:17], v[72:73], v[16:17]
	v_pk_mul_f32 v[20:21], v[78:79], v[20:21]
	v_pk_fma_f32 v[12:13], v[12:13], v[84:85], v[18:19]
	v_mul_f32_e32 v18, 0xbfb8aa3b, v14
	v_mul_f32_e32 v19, 0xbfb8aa3b, v15
	v_pk_fma_f32 v[10:11], v[10:11], v[82:83], v[20:21]
	v_exp_f32_e32 v18, v18
	v_exp_f32_e32 v19, v19
	v_mul_f32_e32 v20, 0xbfb8aa3b, v16
	v_mul_f32_e32 v21, 0xbfb8aa3b, v17
	v_exp_f32_e32 v20, v20
	v_exp_f32_e32 v21, v21
	v_add_f32_e32 v18, 1.0, v18
	v_add_f32_e32 v19, 1.0, v19
	v_rcp_f32_e32 v18, v18
	v_rcp_f32_e32 v19, v19
	v_add_f32_e32 v20, 1.0, v20
	v_add_f32_e32 v21, 1.0, v21
	v_mov_b32_dpp v46, v2 row_ror:15 row_mask:0xf bank_mask:0xf
	v_mov_b32_dpp v47, v3 row_ror:15 row_mask:0xf bank_mask:0xf
	v_rcp_f32_e32 v20, v20
	v_rcp_f32_e32 v21, v21
	v_mov_b32_dpp v48, v4 row_ror:15 row_mask:0xf bank_mask:0xf
	v_mov_b32_dpp v49, v5 row_ror:15 row_mask:0xf bank_mask:0xf
	v_cndmask_b32_e64 v25, v91, v47, s[40:41]
	v_cndmask_b32_e64 v24, v90, v46, s[40:41]
	v_cndmask_b32_e64 v23, v93, v49, s[40:41]
	v_cndmask_b32_e64 v22, v92, v48, s[40:41]
	v_pk_fma_f32 v[10:11], v[58:59], v[24:25], v[10:11]
	v_pk_fma_f32 v[12:13], v[60:61], v[22:23], v[12:13]
	v_pk_add_f32 v[10:11], v[86:87], v[10:11]
	v_pk_mul_f32 v[14:15], v[14:15], v[18:19]
	v_pk_add_f32 v[12:13], v[88:89], v[12:13]
	v_pk_mul_f32 v[10:11], v[14:15], v[10:11]
	v_pk_mul_f32 v[14:15], v[16:17], v[20:21]
	v_cvt_pk_bf16_f32 v10, v10, v11
	v_pk_mul_f32 v[12:13], v[14:15], v[12:13]
	v_cvt_pk_bf16_f32 v11, v12, v13
	global_store_dwordx2 v[110:111], v[10:11], off offset:8
	v_mov_b32_dpp v10, v6 row_ror:1 row_mask:0xf bank_mask:0xf
	v_mov_b32_dpp v11, v7 row_ror:1 row_mask:0xf bank_mask:0xf
	v_mov_b32_dpp v12, v8 row_ror:1 row_mask:0xf bank_mask:0xf
	v_cndmask_b32_e64 v11, v11, v27, s[42:43]
	v_mov_b32_dpp v13, v9 row_ror:1 row_mask:0xf bank_mask:0xf
	v_cndmask_b32_e64 v10, v10, v26, s[42:43]
	v_cndmask_b32_e64 v13, v13, v29, s[42:43]
	v_cndmask_b32_e64 v12, v12, v28, s[42:43]
	v_pk_mul_f32 v[10:11], v[66:67], v[10:11]
	v_mov_b32_dpp v16, v4 row_ror:1 row_mask:0xf bank_mask:0xf
	v_mov_b32_dpp v17, v5 row_ror:1 row_mask:0xf bank_mask:0xf
	v_pk_mul_f32 v[12:13], v[68:69], v[12:13]
	v_pk_fma_f32 v[6:7], v[6:7], v[74:75], v[10:11]
	v_cndmask_b32_e64 v11, v31, v35, s[40:41]
	v_cndmask_b32_e64 v10, v30, v34, s[40:41]
	v_mov_b32_dpp v14, v2 row_ror:1 row_mask:0xf bank_mask:0xf
	v_mov_b32_dpp v15, v3 row_ror:1 row_mask:0xf bank_mask:0xf
	v_pk_fma_f32 v[8:9], v[8:9], v[76:77], v[12:13]
	v_cndmask_b32_e64 v13, v33, v37, s[40:41]
	v_cndmask_b32_e64 v12, v32, v36, s[40:41]
	v_pk_fma_f32 v[6:7], v[62:63], v[10:11], v[6:7]
	v_cndmask_b32_e64 v11, v17, v45, s[42:43]
	v_cndmask_b32_e64 v10, v16, v44, s[42:43]
	v_pk_fma_f32 v[8:9], v[64:65], v[12:13], v[8:9]
	v_pk_add_f32 v[6:7], v[70:71], v[6:7]
	v_cndmask_b32_e64 v13, v15, v43, s[42:43]
	v_cndmask_b32_e64 v12, v14, v42, s[42:43]
	v_pk_mul_f32 v[10:11], v[80:81], v[10:11]
	v_pk_add_f32 v[8:9], v[72:73], v[8:9]
	v_pk_mul_f32 v[12:13], v[78:79], v[12:13]
	v_pk_fma_f32 v[4:5], v[4:5], v[84:85], v[10:11]
	v_mul_f32_e32 v10, 0xbfb8aa3b, v6
	v_mul_f32_e32 v11, 0xbfb8aa3b, v7
	v_pk_fma_f32 v[2:3], v[2:3], v[82:83], v[12:13]
	v_exp_f32_e32 v10, v10
	v_exp_f32_e32 v11, v11
	v_mul_f32_e32 v12, 0xbfb8aa3b, v8
	v_mul_f32_e32 v13, 0xbfb8aa3b, v9
	v_exp_f32_e32 v12, v12
	v_exp_f32_e32 v13, v13
	v_add_f32_e32 v10, 1.0, v10
	v_add_f32_e32 v11, 1.0, v11
	v_rcp_f32_e32 v10, v10
	v_rcp_f32_e32 v11, v11
	v_add_f32_e32 v12, 1.0, v12
	v_add_f32_e32 v13, 1.0, v13
	v_rcp_f32_e32 v12, v12
	v_rcp_f32_e32 v13, v13
	v_cndmask_b32_e64 v17, v47, v39, s[40:41]
	v_cndmask_b32_e64 v16, v46, v38, s[40:41]
	v_cndmask_b32_e64 v15, v49, v41, s[40:41]
	v_cndmask_b32_e64 v14, v48, v40, s[40:41]
	v_pk_fma_f32 v[2:3], v[58:59], v[16:17], v[2:3]
	v_pk_fma_f32 v[4:5], v[60:61], v[14:15], v[4:5]
	v_pk_add_f32 v[2:3], v[86:87], v[2:3]
	v_pk_mul_f32 v[6:7], v[6:7], v[10:11]
	v_pk_add_f32 v[4:5], v[88:89], v[4:5]
	v_pk_mul_f32 v[2:3], v[2:3], v[6:7]
	v_pk_mul_f32 v[6:7], v[8:9], v[12:13]
	v_cvt_pk_bf16_f32 v2, v2, v3
	v_pk_mul_f32 v[4:5], v[4:5], v[6:7]
	s_and_b64 vcc, exec, s[38:39]
	v_cvt_pk_bf16_f32 v3, v4, v5
	s_mov_b64 s[0:1], -1
	global_store_dwordx2 v[98:99], v[2:3], off offset:8
	s_cbranch_vccnz .LBB0_64
	s_andn2_b64 vcc, exec, s[6:7]
	s_cbranch_vccnz .LBB0_63
	s_barrier
	s_branch .LBB0_63

.LBB0_1100:
	v_readlane_b32 s2, v254, 21
	s_add_i32 s8, s2, 1
	s_cmp_ge_i32 s8, s89
	v_readlane_b32 s6, v254, 24
	s_cselect_b64 s[0:1], -1, 0
	s_and_b32 s22, 0xffff, s6
	s_cmp_eq_u32 s22, 9
	s_cselect_b64 s[22:23], -1, 0
	s_or_b64 s[22:23], s[0:1], s[22:23]
	s_and_b64 vcc, exec, s[22:23]
	v_readlane_b32 s44, v254, 8
	v_readlane_b32 s14, v254, 12
	v_readlane_b32 s36, v254, 14
	v_readlane_b32 s45, v254, 9
	v_readlane_b32 s12, v254, 10
	v_readlane_b32 s13, v254, 11
	v_readlane_b32 s15, v254, 13
	v_readlane_b32 s37, v254, 15
	s_cbranch_vccnz .LBB0_10
	s_cmp_lg_u32 s2, s88
	s_mov_b64 s[22:23], -1
	s_waitcnt vmcnt(0)
	v_readlane_b32 s6, v251, 19
	v_readlane_b32 s7, v251, 20
	s_waitcnt vmcnt(0) lgkmcnt(0)
	s_barrier
	s_and_saveexec_b64 s[22:23], s[6:7]
	v_readlane_b32 s6, v251, 48
	s_cbranch_execz .LBB0_1154
	v_readlane_b32 s2, v253, 43
	s_waitcnt vmcnt(0) expcnt(0) lgkmcnt(0)
	s_nop 0
	v_mov_b32_e32 v0, s2
	ds_read_b32 v3, v0
	v_readlane_b32 s2, v253, 44
	s_waitcnt lgkmcnt(0)
	v_cmp_ne_u32_e32 vcc, 0, v3
	v_mov_b32_e32 v0, s2
	ds_read_b32 v2, v0
	s_cbranch_vccnz .LBB0_1118
	s_mov_b32 s28, 1
	s_branch .LBB0_1106
